# early final RMSNorm (rows<16384) on non-tail workgroups beside last down-GEMM tail; down-GEMM xb stores write-through; arrival counter hand-off
# speedup vs baseline: 1.0162x; 1.0030x over previous
; __device__ __forceinline__ unsigned cvt_pk_bf16(float lo, float hi) { const bf16x2_t r = __builtin_convertvector((f32x2){lo, hi}, bf16x2_t); return __builtin_bit_cast(unsigned, r); }
;     __device__ __forceinline__ void operator()(f32x4 (&acc)[2][2][4][2], const Unit& u, int row0t, int wr, int wc, int fr, int fq) const {
;     ...
;         const int row0 = row0t + wr * 64 + fr, col0 = u.pn * BM + wc * 32 + 8 * fq;
; #pragma unroll
;         for (int ai = 0; ai < 2; ++ai) { if (ai == 1 && u.q != 0) break;
; #pragma unroll
;             for (int m = 0; m < 4; ++m) { const int r = row0 + ai * HALF + m * 16; bf16_t* rowp = xb + (size_t)r * D + col0;
;                 const float* src = FIRST ? x0_row(xp, xs, meta, r) : nullptr; float ss = 0.f;
; #pragma unroll
;                 for (int bj = 0; bj < 2; ++bj) { f32x4 b0 = (f32x4){0.f, 0.f, 0.f, 0.f}, b1 = b0;
;                     if (FIRST) { if (src) { b0 = __builtin_nontemporal_load((const f32x4*)(src + col0 + bj * HALF)); b1 = __builtin_nontemporal_load((const f32x4*)(src + col0 + bj * HALF + 4)); } }
;                     else { const u32x4 w = *(const u32x4*)(rowp + bj * HALF);
;                         b0 = (f32x4){__uint_as_float(w.x << 16), __uint_as_float(w.x & 0xffff0000u), __uint_as_float(w.y << 16), __uint_as_float(w.y & 0xffff0000u)};
;                         b1 = (f32x4){__uint_as_float(w.z << 16), __uint_as_float(w.z & 0xffff0000u), __uint_as_float(w.w << 16), __uint_as_float(w.w & 0xffff0000u)}; }
;                     const f32x4 v0 = acc[ai][bj][m][0] + b0, v1 = acc[ai][bj][m][1] + b1;
;                     ss += ((v0[0] * v0[0] + v0[1] * v0[1]) + (v0[2] * v0[2] + v0[3] * v0[3])) + ((v1[0] * v1[0] + v1[1] * v1[1]) + (v1[2] * v1[2] + v1[3] * v1[3]));
;                     u32x4 o; o.x = cvt_pk_bf16(v0[0], v0[1]); o.y = cvt_pk_bf16(v0[2], v0[3]); o.z = cvt_pk_bf16(v1[0], v1[1]); o.w = cvt_pk_bf16(v1[2], v1[3]);
;                     *(u32x4*)(rowp + bj * HALF) = o; }
;                 if (rss) { ss += __shfl_xor(ss, 16); ss += __shfl_xor(ss, 32); if (fq == 0) atomicAdd(rss + r, ss); }
.LBB0_1468:
	s_and_b64 vcc, exec, s[10:11]
	s_cbranch_vccz .LBB0_1486
	s_lshl_b32 s50, s64, 8
	s_cmp_lg_u32 s63, 0
	s_cselect_b64 s[10:11], -1, 0
	s_cmp_eq_u32 s65, 0
	s_cselect_b64 s[48:49], -1, 0
	s_and_b64 s[10:11], s[10:11], s[48:49]
	s_and_b64 s[10:11], s[10:11], exec
	s_cselect_b32 s10, 0x80, 0
	s_or_b32 s10, s10, s50
	v_add_u32_e32 v20, s10, v231
	v_ashrrev_i32_e32 v21, 31, v20
	v_lshl_or_b32 v136, s62, 8, v233
	v_lshlrev_b64 v[134:135], 11, v[20:21]
	v_ashrrev_i32_e32 v137, 31, v136
	v_lshl_add_u64 v[134:135], s[44:45], 0, v[134:135]
	v_lshl_add_u64 v[134:135], v[136:137], 1, v[134:135]
	global_load_dwordx4 v[138:141], v[134:135], off
	v_cndmask_b32_e64 v18, 0, 1, s[38:39]
	v_cmp_ne_u32_e64 s[10:11], 1, v18
	s_andn2_b64 vcc, exec, s[38:39]
	s_waitcnt vmcnt(0)
	v_lshlrev_b32_e32 v142, 16, v138
	v_and_b32_e32 v143, 0xffff0000, v138
	v_lshlrev_b32_e32 v138, 16, v139
	v_and_b32_e32 v139, 0xffff0000, v139
	v_lshlrev_b32_e32 v144, 16, v140
	v_and_b32_e32 v145, 0xffff0000, v140
	v_lshlrev_b32_e32 v146, 16, v141
	v_and_b32_e32 v147, 0xffff0000, v141
	v_pk_add_f32 v[138:139], v[128:129], v[138:139]
	v_pk_add_f32 v[140:141], v[126:127], v[142:143]
	v_pk_add_f32 v[126:127], v[132:133], v[146:147]
	v_pk_add_f32 v[128:129], v[130:131], v[144:145]
	v_cvt_pk_bf16_f32 v130, v140, v141
	v_cvt_pk_bf16_f32 v131, v138, v139
	v_cvt_pk_bf16_f32 v132, v128, v129
	v_cvt_pk_bf16_f32 v133, v126, v127
	global_store_dwordx4 v[134:135], v[130:133], off sc0 sc1
	global_load_dwordx4 v[130:133], v[134:135], off offset:256
	s_waitcnt vmcnt(0)
	v_lshlrev_b32_e32 v142, 16, v130
	v_and_b32_e32 v143, 0xffff0000, v130
	v_lshlrev_b32_e32 v130, 16, v131
	v_and_b32_e32 v131, 0xffff0000, v131
	v_lshlrev_b32_e32 v144, 16, v132
	v_and_b32_e32 v145, 0xffff0000, v132
	v_lshlrev_b32_e32 v132, 16, v133
	v_and_b32_e32 v133, 0xffff0000, v133
	v_pk_add_f32 v[124:125], v[124:125], v[130:131]
	v_pk_add_f32 v[122:123], v[122:123], v[142:143]
	v_pk_add_f32 v[120:121], v[120:121], v[132:133]
	v_pk_add_f32 v[118:119], v[118:119], v[144:145]
	v_cvt_pk_bf16_f32 v130, v122, v123
	v_cvt_pk_bf16_f32 v131, v124, v125
	v_cvt_pk_bf16_f32 v132, v118, v119
	v_cvt_pk_bf16_f32 v133, v120, v121
	global_store_dwordx4 v[134:135], v[130:133], off offset:256 sc0 sc1
	s_cbranch_vccnz .LBB0_1473
	v_mul_f32_e32 v123, v123, v123
	v_mul_f32_e32 v119, v119, v119
	v_mul_f32_e32 v18, v141, v141
	v_mul_f32_e32 v130, v139, v139
	v_mul_f32_e32 v129, v129, v129
	v_mul_f32_e32 v127, v127, v127
	v_fmac_f32_e32 v123, v122, v122
	v_mul_f32_e32 v122, v125, v125
	v_fmac_f32_e32 v119, v118, v118
	v_mul_f32_e32 v118, v121, v121
	v_fmac_f32_e32 v18, v140, v140
	v_fmac_f32_e32 v130, v138, v138
	v_fmac_f32_e32 v129, v128, v128
	v_fmac_f32_e32 v127, v126, v126
	v_fmac_f32_e32 v122, v124, v124
	v_fmac_f32_e32 v118, v120, v120
	v_add_f32_e32 v18, v18, v130
	v_add_f32_e32 v126, v129, v127
	v_add_f32_e32 v122, v123, v122
	v_add_f32_e32 v118, v119, v118
	v_add_f32_e32 v18, v18, v126
	v_add_f32_e32 v118, v122, v118
	v_and_b32_e32 v119, 64, v226
	v_add_f32_e32 v18, v18, v118
	v_xor_b32_e32 v118, 16, v226
	v_add_u32_e32 v119, 64, v119
	v_cmp_lt_i32_e32 vcc, v118, v119
	s_nop 1
	v_cndmask_b32_e32 v118, v226, v118, vcc
	v_lshlrev_b32_e32 v118, 2, v118
	ds_bpermute_b32 v118, v118, v18
	s_waitcnt lgkmcnt(0)
	v_add_f32_e32 v18, v18, v118
	v_xor_b32_e32 v118, 32, v226
	v_cmp_lt_i32_e32 vcc, v118, v119
	s_nop 1
	v_cndmask_b32_e32 v118, v226, v118, vcc
	v_lshlrev_b32_e32 v118, 2, v118
	ds_bpermute_b32 v118, v118, v18
	s_and_saveexec_b64 s[48:49], s[6:7]
	s_cbranch_execz .LBB0_1472
	v_lshl_add_u64 v[120:121], v[20:21], 2, s[24:25]
	s_waitcnt lgkmcnt(0)
	v_add_f32_e32 v18, v18, v118
	global_atomic_add_f32 v[120:121], v18, off

; __device__ __forceinline__ unsigned cvt_pk_bf16(float lo, float hi) { const bf16x2_t r = __builtin_convertvector((f32x2){lo, hi}, bf16x2_t); return __builtin_bit_cast(unsigned, r); }
;     __device__ __forceinline__ void operator()(f32x4 (&acc)[2][2][4][2], const Unit& u, int row0t, int wr, int wc, int fr, int fq) const {
;     ...
;         const int row0 = row0t + wr * 64 + fr, col0 = u.pn * BM + wc * 32 + 8 * fq;
; #pragma unroll
;         for (int ai = 0; ai < 2; ++ai) { if (ai == 1 && u.q != 0) break;
; #pragma unroll
;             for (int m = 0; m < 4; ++m) { const int r = row0 + ai * HALF + m * 16; bf16_t* rowp = xb + (size_t)r * D + col0;
;                 const float* src = FIRST ? x0_row(xp, xs, meta, r) : nullptr; float ss = 0.f;
; #pragma unroll
;                 for (int bj = 0; bj < 2; ++bj) { f32x4 b0 = (f32x4){0.f, 0.f, 0.f, 0.f}, b1 = b0;
;                     if (FIRST) { if (src) { b0 = __builtin_nontemporal_load((const f32x4*)(src + col0 + bj * HALF)); b1 = __builtin_nontemporal_load((const f32x4*)(src + col0 + bj * HALF + 4)); } }
;                     else { const u32x4 w = *(const u32x4*)(rowp + bj * HALF);
;                         b0 = (f32x4){__uint_as_float(w.x << 16), __uint_as_float(w.x & 0xffff0000u), __uint_as_float(w.y << 16), __uint_as_float(w.y & 0xffff0000u)};
;                         b1 = (f32x4){__uint_as_float(w.z << 16), __uint_as_float(w.z & 0xffff0000u), __uint_as_float(w.w << 16), __uint_as_float(w.w & 0xffff0000u)}; }
;                     const f32x4 v0 = acc[ai][bj][m][0] + b0, v1 = acc[ai][bj][m][1] + b1;
;                     ss += ((v0[0] * v0[0] + v0[1] * v0[1]) + (v0[2] * v0[2] + v0[3] * v0[3])) + ((v1[0] * v1[0] + v1[1] * v1[1]) + (v1[2] * v1[2] + v1[3] * v1[3]));
;                     u32x4 o; o.x = cvt_pk_bf16(v0[0], v0[1]); o.y = cvt_pk_bf16(v0[2], v0[3]); o.z = cvt_pk_bf16(v1[0], v1[1]); o.w = cvt_pk_bf16(v1[2], v1[3]);
;                     *(u32x4*)(rowp + bj * HALF) = o; }
;                 if (rss) { ss += __shfl_xor(ss, 16); ss += __shfl_xor(ss, 32); if (fq == 0) atomicAdd(rss + r, ss); }
.LBB0_1473:
	s_waitcnt lgkmcnt(0)
	v_or_b32_e32 v118, 16, v20
	v_ashrrev_i32_e32 v119, 31, v118
	v_lshlrev_b64 v[118:119], 11, v[118:119]
	v_lshl_add_u64 v[118:119], s[44:45], 0, v[118:119]
	v_lshl_add_u64 v[122:123], v[136:137], 1, v[118:119]
	global_load_dwordx4 v[118:121], v[122:123], off
	s_and_b64 vcc, exec, s[10:11]
	s_waitcnt vmcnt(0)
	v_lshlrev_b32_e32 v124, 16, v118
	v_and_b32_e32 v125, 0xffff0000, v118
	v_lshlrev_b32_e32 v118, 16, v119
	v_and_b32_e32 v119, 0xffff0000, v119
	v_lshlrev_b32_e32 v126, 16, v120
	v_and_b32_e32 v127, 0xffff0000, v120
	v_lshlrev_b32_e32 v120, 16, v121
	v_and_b32_e32 v121, 0xffff0000, v121
	v_pk_add_f32 v[116:117], v[116:117], v[118:119]
	v_pk_add_f32 v[114:115], v[114:115], v[124:125]
	v_pk_add_f32 v[112:113], v[112:113], v[120:121]
	v_pk_add_f32 v[110:111], v[110:111], v[126:127]
	v_cvt_pk_bf16_f32 v118, v114, v115
	v_cvt_pk_bf16_f32 v119, v116, v117
	v_cvt_pk_bf16_f32 v120, v110, v111
	v_cvt_pk_bf16_f32 v121, v112, v113
	global_store_dwordx4 v[122:123], v[118:121], off sc0 sc1
	global_load_dwordx4 v[118:121], v[122:123], off offset:256
	s_waitcnt vmcnt(0)
	v_lshlrev_b32_e32 v124, 16, v118
	v_and_b32_e32 v125, 0xffff0000, v118
	v_lshlrev_b32_e32 v118, 16, v119
	v_and_b32_e32 v119, 0xffff0000, v119
	v_lshlrev_b32_e32 v126, 16, v120
	v_and_b32_e32 v127, 0xffff0000, v120
	v_lshlrev_b32_e32 v120, 16, v121
	v_and_b32_e32 v121, 0xffff0000, v121
	v_pk_add_f32 v[108:109], v[108:109], v[118:119]
	v_pk_add_f32 v[106:107], v[106:107], v[124:125]
	v_pk_add_f32 v[104:105], v[104:105], v[120:121]
	v_pk_add_f32 v[102:103], v[102:103], v[126:127]
	v_cvt_pk_bf16_f32 v118, v106, v107
	v_cvt_pk_bf16_f32 v119, v108, v109
	v_cvt_pk_bf16_f32 v120, v102, v103
	v_cvt_pk_bf16_f32 v121, v104, v105
	global_store_dwordx4 v[122:123], v[118:121], off offset:256 sc0 sc1
	s_cbranch_vccnz .LBB0_1477
	v_mul_f32_e32 v18, v115, v115
	v_mul_f32_e32 v111, v111, v111
	v_mul_f32_e32 v107, v107, v107
	v_mul_f32_e32 v103, v103, v103
	v_fmac_f32_e32 v18, v114, v114
	v_mul_f32_e32 v114, v117, v117
	v_fmac_f32_e32 v111, v110, v110
	v_mul_f32_e32 v110, v113, v113
	v_fmac_f32_e32 v107, v106, v106
	v_mul_f32_e32 v106, v109, v109
	v_fmac_f32_e32 v103, v102, v102
	v_mul_f32_e32 v102, v105, v105
	v_fmac_f32_e32 v114, v116, v116
	v_fmac_f32_e32 v110, v112, v112
	v_fmac_f32_e32 v106, v108, v108
	v_fmac_f32_e32 v102, v104, v104
	v_add_f32_e32 v18, v18, v114
	v_add_f32_e32 v110, v111, v110
	v_add_f32_e32 v106, v107, v106
	v_add_f32_e32 v102, v103, v102
	v_add_f32_e32 v18, v18, v110
	v_add_f32_e32 v102, v106, v102
	v_and_b32_e32 v103, 64, v226
	v_add_f32_e32 v18, v18, v102
	v_xor_b32_e32 v102, 16, v226
	v_add_u32_e32 v103, 64, v103
	v_cmp_lt_i32_e32 vcc, v102, v103
	s_nop 1
	v_cndmask_b32_e32 v102, v226, v102, vcc
	v_lshlrev_b32_e32 v102, 2, v102
	ds_bpermute_b32 v102, v102, v18
	s_waitcnt lgkmcnt(0)
	v_add_f32_e32 v18, v18, v102
	v_xor_b32_e32 v102, 32, v226
	v_cmp_lt_i32_e32 vcc, v102, v103
	s_nop 1
	v_cndmask_b32_e32 v102, v226, v102, vcc
	v_lshlrev_b32_e32 v102, 2, v102
	ds_bpermute_b32 v102, v102, v18
	s_and_saveexec_b64 s[48:49], s[6:7]
	s_cbranch_execz .LBB0_1476
	v_lshl_add_u64 v[104:105], v[20:21], 2, s[24:25]
	s_waitcnt lgkmcnt(0)
	v_add_f32_e32 v18, v18, v102
	global_atomic_add_f32 v[104:105], v18, off offset:64

; __device__ __forceinline__ unsigned cvt_pk_bf16(float lo, float hi) { const bf16x2_t r = __builtin_convertvector((f32x2){lo, hi}, bf16x2_t); return __builtin_bit_cast(unsigned, r); }
;     __device__ __forceinline__ void operator()(f32x4 (&acc)[2][2][4][2], const Unit& u, int row0t, int wr, int wc, int fr, int fq) const {
;     ...
;         const int row0 = row0t + wr * 64 + fr, col0 = u.pn * BM + wc * 32 + 8 * fq;
; #pragma unroll
;         for (int ai = 0; ai < 2; ++ai) { if (ai == 1 && u.q != 0) break;
; #pragma unroll
;             for (int m = 0; m < 4; ++m) { const int r = row0 + ai * HALF + m * 16; bf16_t* rowp = xb + (size_t)r * D + col0;
;                 const float* src = FIRST ? x0_row(xp, xs, meta, r) : nullptr; float ss = 0.f;
; #pragma unroll
;                 for (int bj = 0; bj < 2; ++bj) { f32x4 b0 = (f32x4){0.f, 0.f, 0.f, 0.f}, b1 = b0;
;                     if (FIRST) { if (src) { b0 = __builtin_nontemporal_load((const f32x4*)(src + col0 + bj * HALF)); b1 = __builtin_nontemporal_load((const f32x4*)(src + col0 + bj * HALF + 4)); } }
;                     else { const u32x4 w = *(const u32x4*)(rowp + bj * HALF);
;                         b0 = (f32x4){__uint_as_float(w.x << 16), __uint_as_float(w.x & 0xffff0000u), __uint_as_float(w.y << 16), __uint_as_float(w.y & 0xffff0000u)};
;                         b1 = (f32x4){__uint_as_float(w.z << 16), __uint_as_float(w.z & 0xffff0000u), __uint_as_float(w.w << 16), __uint_as_float(w.w & 0xffff0000u)}; }
;                     const f32x4 v0 = acc[ai][bj][m][0] + b0, v1 = acc[ai][bj][m][1] + b1;
;                     ss += ((v0[0] * v0[0] + v0[1] * v0[1]) + (v0[2] * v0[2] + v0[3] * v0[3])) + ((v1[0] * v1[0] + v1[1] * v1[1]) + (v1[2] * v1[2] + v1[3] * v1[3]));
;                     u32x4 o; o.x = cvt_pk_bf16(v0[0], v0[1]); o.y = cvt_pk_bf16(v0[2], v0[3]); o.z = cvt_pk_bf16(v1[0], v1[1]); o.w = cvt_pk_bf16(v1[2], v1[3]);
;                     *(u32x4*)(rowp + bj * HALF) = o; }
;                 if (rss) { ss += __shfl_xor(ss, 16); ss += __shfl_xor(ss, 32); if (fq == 0) atomicAdd(rss + r, ss); }
.LBB0_1477:
	s_waitcnt lgkmcnt(0)
	v_or_b32_e32 v102, 32, v20
	v_ashrrev_i32_e32 v103, 31, v102
	v_lshlrev_b64 v[102:103], 11, v[102:103]
	v_lshl_add_u64 v[102:103], s[44:45], 0, v[102:103]
	v_lshl_add_u64 v[106:107], v[136:137], 1, v[102:103]
	global_load_dwordx4 v[102:105], v[106:107], off
	s_and_b64 vcc, exec, s[10:11]
	s_waitcnt vmcnt(0)
	v_lshlrev_b32_e32 v108, 16, v102
	v_and_b32_e32 v109, 0xffff0000, v102
	v_lshlrev_b32_e32 v102, 16, v103
	v_and_b32_e32 v103, 0xffff0000, v103
	v_lshlrev_b32_e32 v110, 16, v104
	v_and_b32_e32 v111, 0xffff0000, v104
	v_lshlrev_b32_e32 v104, 16, v105
	v_and_b32_e32 v105, 0xffff0000, v105
	v_pk_add_f32 v[100:101], v[100:101], v[102:103]
	v_pk_add_f32 v[98:99], v[98:99], v[108:109]
	v_pk_add_f32 v[96:97], v[96:97], v[104:105]
	v_pk_add_f32 v[94:95], v[94:95], v[110:111]
	v_cvt_pk_bf16_f32 v102, v98, v99
	v_cvt_pk_bf16_f32 v103, v100, v101
	v_cvt_pk_bf16_f32 v104, v94, v95
	v_cvt_pk_bf16_f32 v105, v96, v97
	global_store_dwordx4 v[106:107], v[102:105], off sc0 sc1
	global_load_dwordx4 v[102:105], v[106:107], off offset:256
	s_waitcnt vmcnt(0)
	v_lshlrev_b32_e32 v108, 16, v102
	v_and_b32_e32 v109, 0xffff0000, v102
	v_lshlrev_b32_e32 v102, 16, v103
	v_and_b32_e32 v103, 0xffff0000, v103
	v_lshlrev_b32_e32 v110, 16, v104
	v_and_b32_e32 v111, 0xffff0000, v104
	v_lshlrev_b32_e32 v104, 16, v105
	v_and_b32_e32 v105, 0xffff0000, v105
	v_pk_add_f32 v[92:93], v[92:93], v[102:103]
	v_pk_add_f32 v[90:91], v[90:91], v[108:109]
	v_pk_add_f32 v[88:89], v[88:89], v[104:105]
	v_pk_add_f32 v[86:87], v[86:87], v[110:111]
	v_cvt_pk_bf16_f32 v102, v90, v91
	v_cvt_pk_bf16_f32 v103, v92, v93
	v_cvt_pk_bf16_f32 v104, v86, v87
	v_cvt_pk_bf16_f32 v105, v88, v89
	global_store_dwordx4 v[106:107], v[102:105], off offset:256 sc0 sc1
	s_cbranch_vccnz .LBB0_1481
	v_mul_f32_e32 v18, v99, v99
	v_mul_f32_e32 v95, v95, v95
	v_mul_f32_e32 v91, v91, v91
	v_mul_f32_e32 v87, v87, v87
	v_fmac_f32_e32 v18, v98, v98
	v_mul_f32_e32 v98, v101, v101
	v_fmac_f32_e32 v95, v94, v94
	v_mul_f32_e32 v94, v97, v97
	v_fmac_f32_e32 v91, v90, v90
	v_mul_f32_e32 v90, v93, v93
	v_fmac_f32_e32 v87, v86, v86
	v_mul_f32_e32 v86, v89, v89
	v_fmac_f32_e32 v98, v100, v100
	v_fmac_f32_e32 v94, v96, v96
	v_fmac_f32_e32 v90, v92, v92
	v_fmac_f32_e32 v86, v88, v88
	v_add_f32_e32 v18, v18, v98
	v_add_f32_e32 v94, v95, v94
	v_add_f32_e32 v90, v91, v90
	v_add_f32_e32 v86, v87, v86
	v_add_f32_e32 v18, v18, v94
	v_add_f32_e32 v86, v90, v86
	v_and_b32_e32 v87, 64, v226
	v_add_f32_e32 v18, v18, v86
	v_xor_b32_e32 v86, 16, v226
	v_add_u32_e32 v87, 64, v87
	v_cmp_lt_i32_e32 vcc, v86, v87
	s_nop 1
	v_cndmask_b32_e32 v86, v226, v86, vcc
	v_lshlrev_b32_e32 v86, 2, v86
	ds_bpermute_b32 v86, v86, v18
	s_waitcnt lgkmcnt(0)
	v_add_f32_e32 v18, v18, v86
	v_xor_b32_e32 v86, 32, v226
	v_cmp_lt_i32_e32 vcc, v86, v87
	s_nop 1
	v_cndmask_b32_e32 v86, v226, v86, vcc
	v_lshlrev_b32_e32 v86, 2, v86
	ds_bpermute_b32 v86, v86, v18
	s_and_saveexec_b64 s[48:49], s[6:7]
	s_cbranch_execz .LBB0_1480
	v_lshl_add_u64 v[88:89], v[20:21], 2, s[24:25]
	s_waitcnt lgkmcnt(0)
	v_add_f32_e32 v18, v18, v86
	global_atomic_add_f32 v[88:89], v18, off offset:128

; __device__ __forceinline__ unsigned cvt_pk_bf16(float lo, float hi) { const bf16x2_t r = __builtin_convertvector((f32x2){lo, hi}, bf16x2_t); return __builtin_bit_cast(unsigned, r); }
;     __device__ __forceinline__ void operator()(f32x4 (&acc)[2][2][4][2], const Unit& u, int row0t, int wr, int wc, int fr, int fq) const {
;     ...
;         const int row0 = row0t + wr * 64 + fr, col0 = u.pn * BM + wc * 32 + 8 * fq;
; #pragma unroll
;         for (int ai = 0; ai < 2; ++ai) { if (ai == 1 && u.q != 0) break;
; #pragma unroll
;             for (int m = 0; m < 4; ++m) { const int r = row0 + ai * HALF + m * 16; bf16_t* rowp = xb + (size_t)r * D + col0;
;                 const float* src = FIRST ? x0_row(xp, xs, meta, r) : nullptr; float ss = 0.f;
; #pragma unroll
;                 for (int bj = 0; bj < 2; ++bj) { f32x4 b0 = (f32x4){0.f, 0.f, 0.f, 0.f}, b1 = b0;
;                     if (FIRST) { if (src) { b0 = __builtin_nontemporal_load((const f32x4*)(src + col0 + bj * HALF)); b1 = __builtin_nontemporal_load((const f32x4*)(src + col0 + bj * HALF + 4)); } }
;                     else { const u32x4 w = *(const u32x4*)(rowp + bj * HALF);
;                         b0 = (f32x4){__uint_as_float(w.x << 16), __uint_as_float(w.x & 0xffff0000u), __uint_as_float(w.y << 16), __uint_as_float(w.y & 0xffff0000u)};
;                         b1 = (f32x4){__uint_as_float(w.z << 16), __uint_as_float(w.z & 0xffff0000u), __uint_as_float(w.w << 16), __uint_as_float(w.w & 0xffff0000u)}; }
;                     const f32x4 v0 = acc[ai][bj][m][0] + b0, v1 = acc[ai][bj][m][1] + b1;
;                     ss += ((v0[0] * v0[0] + v0[1] * v0[1]) + (v0[2] * v0[2] + v0[3] * v0[3])) + ((v1[0] * v1[0] + v1[1] * v1[1]) + (v1[2] * v1[2] + v1[3] * v1[3]));
;                     u32x4 o; o.x = cvt_pk_bf16(v0[0], v0[1]); o.y = cvt_pk_bf16(v0[2], v0[3]); o.z = cvt_pk_bf16(v1[0], v1[1]); o.w = cvt_pk_bf16(v1[2], v1[3]);
;                     *(u32x4*)(rowp + bj * HALF) = o; }
;                 if (rss) { ss += __shfl_xor(ss, 16); ss += __shfl_xor(ss, 32); if (fq == 0) atomicAdd(rss + r, ss); }
.LBB0_1481:
	s_waitcnt lgkmcnt(0)
	v_or_b32_e32 v86, 48, v20
	v_ashrrev_i32_e32 v87, 31, v86
	v_lshlrev_b64 v[86:87], 11, v[86:87]
	v_lshl_add_u64 v[86:87], s[44:45], 0, v[86:87]
	v_lshl_add_u64 v[90:91], v[136:137], 1, v[86:87]
	global_load_dwordx4 v[86:89], v[90:91], off
	s_and_b64 vcc, exec, s[10:11]
	s_waitcnt vmcnt(0)
	v_lshlrev_b32_e32 v92, 16, v86
	v_and_b32_e32 v93, 0xffff0000, v86
	v_lshlrev_b32_e32 v86, 16, v87
	v_and_b32_e32 v87, 0xffff0000, v87
	v_lshlrev_b32_e32 v94, 16, v88
	v_and_b32_e32 v95, 0xffff0000, v88
	v_lshlrev_b32_e32 v88, 16, v89
	v_and_b32_e32 v89, 0xffff0000, v89
	v_pk_add_f32 v[84:85], v[84:85], v[86:87]
	v_pk_add_f32 v[82:83], v[82:83], v[92:93]
	v_pk_add_f32 v[80:81], v[80:81], v[88:89]
	v_pk_add_f32 v[78:79], v[78:79], v[94:95]
	v_cvt_pk_bf16_f32 v86, v82, v83
	v_cvt_pk_bf16_f32 v87, v84, v85
	v_cvt_pk_bf16_f32 v88, v78, v79
	v_cvt_pk_bf16_f32 v89, v80, v81
	global_store_dwordx4 v[90:91], v[86:89], off sc0 sc1
	global_load_dwordx4 v[86:89], v[90:91], off offset:256
	s_waitcnt vmcnt(0)
	v_lshlrev_b32_e32 v92, 16, v86
	v_and_b32_e32 v93, 0xffff0000, v86
	v_lshlrev_b32_e32 v86, 16, v87
	v_and_b32_e32 v87, 0xffff0000, v87
	v_lshlrev_b32_e32 v94, 16, v88
	v_and_b32_e32 v95, 0xffff0000, v88
	v_lshlrev_b32_e32 v88, 16, v89
	v_and_b32_e32 v89, 0xffff0000, v89
	v_pk_add_f32 v[76:77], v[76:77], v[86:87]
	v_pk_add_f32 v[74:75], v[74:75], v[92:93]
	v_pk_add_f32 v[72:73], v[72:73], v[88:89]
	v_pk_add_f32 v[70:71], v[70:71], v[94:95]
	v_cvt_pk_bf16_f32 v86, v74, v75
	v_cvt_pk_bf16_f32 v87, v76, v77
	v_cvt_pk_bf16_f32 v88, v70, v71
	v_cvt_pk_bf16_f32 v89, v72, v73
	global_store_dwordx4 v[90:91], v[86:89], off offset:256 sc0 sc1
	s_cbranch_vccnz .LBB0_1485
	v_mul_f32_e32 v18, v83, v83
	v_mul_f32_e32 v79, v79, v79
	v_mul_f32_e32 v75, v75, v75
	v_mul_f32_e32 v71, v71, v71
	v_fmac_f32_e32 v18, v82, v82
	v_mul_f32_e32 v82, v85, v85
	v_fmac_f32_e32 v79, v78, v78
	v_mul_f32_e32 v78, v81, v81
	v_fmac_f32_e32 v75, v74, v74
	v_mul_f32_e32 v74, v77, v77
	v_fmac_f32_e32 v71, v70, v70
	v_mul_f32_e32 v70, v73, v73
	v_fmac_f32_e32 v82, v84, v84
	v_fmac_f32_e32 v78, v80, v80
	v_fmac_f32_e32 v74, v76, v76
	v_fmac_f32_e32 v70, v72, v72
	v_add_f32_e32 v18, v18, v82
	v_add_f32_e32 v78, v79, v78
	v_add_f32_e32 v74, v75, v74
	v_add_f32_e32 v70, v71, v70
	v_add_f32_e32 v18, v18, v78
	v_add_f32_e32 v70, v74, v70
	v_and_b32_e32 v71, 64, v226
	v_add_f32_e32 v18, v18, v70
	v_xor_b32_e32 v70, 16, v226
	v_add_u32_e32 v71, 64, v71
	v_cmp_lt_i32_e32 vcc, v70, v71
	s_nop 1
	v_cndmask_b32_e32 v70, v226, v70, vcc
	v_lshlrev_b32_e32 v70, 2, v70
	ds_bpermute_b32 v70, v70, v18
	s_waitcnt lgkmcnt(0)
	v_add_f32_e32 v18, v18, v70
	v_xor_b32_e32 v70, 32, v226
	v_cmp_lt_i32_e32 vcc, v70, v71
	s_nop 1
	v_cndmask_b32_e32 v70, v226, v70, vcc
	v_lshlrev_b32_e32 v70, 2, v70
	ds_bpermute_b32 v70, v70, v18
	s_and_saveexec_b64 s[48:49], s[6:7]
	s_cbranch_execz .LBB0_1484
	v_lshl_add_u64 v[72:73], v[20:21], 2, s[24:25]
	s_waitcnt lgkmcnt(0)
	v_add_f32_e32 v18, v18, v70
	global_atomic_add_f32 v[72:73], v18, off offset:192

; #define GRID_SYNC() xcd_barrier(xbar)
; __global__ void __launch_bounds__(NTHREADS, 2) fwd_megakernel(Params p) {
;     ...
;             pg8::gemm_phase<pg8::EpiRes<false>, true, true, pg8::TailOrder>(lds, g, S, E);
;         }
;         GRID_SYNC();
.LBB0_1487:
	v_readlane_b32 s98, v239, 0
	s_nop 3
	s_cmp_lg_u32 s98, 0
	s_cbranch_scc1 .Lfn_a1_skip
	s_waitcnt vmcnt(0)
	s_barrier
	v_cmp_eq_u32_e32 vcc, 0, v0
	s_nop 3
	s_mov_b64 exec, vcc
	s_cbranch_execz .Lfn_a1_x
	v_readlane_b32 s98, v245, 33
	v_readlane_b32 s99, v245, 34
	v_mov_b32_e32 v247, 0
	v_mov_b32_e32 v248, 1
	s_nop 3
	s_add_u32 s98, s98, 0xc000
	s_addc_u32 s99, s99, 0
	global_atomic_add v247, v248, s[98:99]
.Lfn_a1_x:
	s_mov_b64 exec, -1

; __device__ __forceinline__ unsigned cvt_pk_bf16(float lo, float hi) { const bf16x2_t r = __builtin_convertvector((f32x2){lo, hi}, bf16x2_t); return __builtin_bit_cast(unsigned, r); }
;     __device__ __forceinline__ void operator()(f32x4 (&acc)[2][2][4][2], const Unit& u, int row0t, int wr, int wc, int fr, int fq) const {
;     ...
;         const int row0 = row0t + wr * 64 + fr, col0 = u.pn * BM + wc * 32 + 8 * fq;
; #pragma unroll
;         for (int ai = 0; ai < 2; ++ai) { if (ai == 1 && u.q != 0) break;
; #pragma unroll
;             for (int m = 0; m < 4; ++m) { const int r = row0 + ai * HALF + m * 16; bf16_t* rowp = xb + (size_t)r * D + col0;
;                 const float* src = FIRST ? x0_row(xp, xs, meta, r) : nullptr; float ss = 0.f;
; #pragma unroll
;                 for (int bj = 0; bj < 2; ++bj) { f32x4 b0 = (f32x4){0.f, 0.f, 0.f, 0.f}, b1 = b0;
;                     if (FIRST) { if (src) { b0 = __builtin_nontemporal_load((const f32x4*)(src + col0 + bj * HALF)); b1 = __builtin_nontemporal_load((const f32x4*)(src + col0 + bj * HALF + 4)); } }
;                     else { const u32x4 w = *(const u32x4*)(rowp + bj * HALF);
;                         b0 = (f32x4){__uint_as_float(w.x << 16), __uint_as_float(w.x & 0xffff0000u), __uint_as_float(w.y << 16), __uint_as_float(w.y & 0xffff0000u)};
;                         b1 = (f32x4){__uint_as_float(w.z << 16), __uint_as_float(w.z & 0xffff0000u), __uint_as_float(w.w << 16), __uint_as_float(w.w & 0xffff0000u)}; }
;                     const f32x4 v0 = acc[ai][bj][m][0] + b0, v1 = acc[ai][bj][m][1] + b1;
;                     ss += ((v0[0] * v0[0] + v0[1] * v0[1]) + (v0[2] * v0[2] + v0[3] * v0[3])) + ((v1[0] * v1[0] + v1[1] * v1[1]) + (v1[2] * v1[2] + v1[3] * v1[3]));
;                     u32x4 o; o.x = cvt_pk_bf16(v0[0], v0[1]); o.y = cvt_pk_bf16(v0[2], v0[3]); o.z = cvt_pk_bf16(v1[0], v1[1]); o.w = cvt_pk_bf16(v1[2], v1[3]);
;                     *(u32x4*)(rowp + bj * HALF) = o; }
;                 if (rss) { ss += __shfl_xor(ss, 16); ss += __shfl_xor(ss, 32); if (fq == 0) atomicAdd(rss + r, ss); }
.LBB0_1489:
	v_add_co_u32_e32 v76, vcc, 0x40000, v134
	s_mov_b64 s[46:47], 0x40000
	s_nop 0
	v_addc_co_u32_e32 v77, vcc, 0, v135, vcc
	s_waitcnt lgkmcnt(0)
	global_load_dwordx4 v[70:73], v[76:77], off
	v_lshl_add_u64 v[74:75], v[134:135], 0, s[46:47]
	s_and_b64 vcc, exec, s[10:11]
	s_waitcnt vmcnt(0)
	v_lshlrev_b32_e32 v78, 16, v70
	v_and_b32_e32 v79, 0xffff0000, v70
	v_lshlrev_b32_e32 v70, 16, v71
	v_and_b32_e32 v71, 0xffff0000, v71
	v_lshlrev_b32_e32 v80, 16, v72
	v_and_b32_e32 v81, 0xffff0000, v72
	v_lshlrev_b32_e32 v82, 16, v73
	v_and_b32_e32 v83, 0xffff0000, v73
	v_pk_add_f32 v[70:71], v[64:65], v[70:71]
	v_pk_add_f32 v[72:73], v[62:63], v[78:79]
	v_pk_add_f32 v[62:63], v[68:69], v[82:83]
	v_pk_add_f32 v[64:65], v[66:67], v[80:81]
	v_cvt_pk_bf16_f32 v66, v72, v73
	v_cvt_pk_bf16_f32 v67, v70, v71
	v_cvt_pk_bf16_f32 v68, v64, v65
	v_cvt_pk_bf16_f32 v69, v62, v63
	global_store_dwordx4 v[76:77], v[66:69], off sc0 sc1
	global_load_dwordx4 v[66:69], v[74:75], off offset:256
	s_waitcnt vmcnt(0)
	v_lshlrev_b32_e32 v76, 16, v66
	v_and_b32_e32 v77, 0xffff0000, v66
	v_lshlrev_b32_e32 v66, 16, v67
	v_and_b32_e32 v67, 0xffff0000, v67
	v_lshlrev_b32_e32 v78, 16, v68
	v_and_b32_e32 v79, 0xffff0000, v68
	v_lshlrev_b32_e32 v80, 16, v69
	v_and_b32_e32 v81, 0xffff0000, v69
	v_pk_add_f32 v[66:67], v[56:57], v[66:67]
	v_pk_add_f32 v[68:69], v[54:55], v[76:77]
	v_pk_add_f32 v[54:55], v[60:61], v[80:81]
	v_pk_add_f32 v[56:57], v[58:59], v[78:79]
	v_cvt_pk_bf16_f32 v58, v68, v69
	v_cvt_pk_bf16_f32 v59, v66, v67
	v_cvt_pk_bf16_f32 v60, v56, v57
	v_cvt_pk_bf16_f32 v61, v54, v55
	global_store_dwordx4 v[74:75], v[58:61], off offset:256 sc0 sc1
	s_cbranch_vccnz .LBB0_1493
	v_mul_f32_e32 v18, v73, v73
	v_mul_f32_e32 v58, v71, v71
	v_fmac_f32_e32 v18, v72, v72
	v_fmac_f32_e32 v58, v70, v70
	v_add_f32_e32 v18, v18, v58
	v_mul_f32_e32 v58, v65, v65
	v_mul_f32_e32 v59, v63, v63
	v_fmac_f32_e32 v58, v64, v64
	v_fmac_f32_e32 v59, v62, v62
	v_add_f32_e32 v58, v58, v59
	v_add_f32_e32 v18, v18, v58
	v_mul_f32_e32 v58, v69, v69
	v_mul_f32_e32 v59, v67, v67
	v_mul_f32_e32 v57, v57, v57
	v_mul_f32_e32 v55, v55, v55
	v_fmac_f32_e32 v58, v68, v68
	v_fmac_f32_e32 v59, v66, v66
	v_fmac_f32_e32 v57, v56, v56
	v_fmac_f32_e32 v55, v54, v54
	v_add_f32_e32 v58, v58, v59
	v_add_f32_e32 v54, v57, v55
	v_add_f32_e32 v54, v58, v54
	v_and_b32_e32 v55, 64, v226
	v_add_f32_e32 v18, v18, v54
	v_xor_b32_e32 v54, 16, v226
	v_add_u32_e32 v55, 64, v55
	v_cmp_lt_i32_e32 vcc, v54, v55
	s_nop 1
	v_cndmask_b32_e32 v54, v226, v54, vcc
	v_lshlrev_b32_e32 v54, 2, v54
	ds_bpermute_b32 v54, v54, v18
	s_waitcnt lgkmcnt(0)
	v_add_f32_e32 v18, v18, v54
	v_xor_b32_e32 v54, 32, v226
	v_cmp_lt_i32_e32 vcc, v54, v55
	s_nop 1
	v_cndmask_b32_e32 v54, v226, v54, vcc
	v_lshlrev_b32_e32 v54, 2, v54
	ds_bpermute_b32 v54, v54, v18
	s_and_saveexec_b64 s[46:47], s[6:7]
	s_cbranch_execz .LBB0_1492
	v_lshl_add_u64 v[56:57], v[20:21], 2, s[24:25]
	s_waitcnt lgkmcnt(0)
	v_add_f32_e32 v18, v18, v54
	global_atomic_add_f32 v[56:57], v18, off offset:512

; __device__ __forceinline__ unsigned cvt_pk_bf16(float lo, float hi) { const bf16x2_t r = __builtin_convertvector((f32x2){lo, hi}, bf16x2_t); return __builtin_bit_cast(unsigned, r); }
;     __device__ __forceinline__ void operator()(f32x4 (&acc)[2][2][4][2], const Unit& u, int row0t, int wr, int wc, int fr, int fq) const {
;     ...
;         const int row0 = row0t + wr * 64 + fr, col0 = u.pn * BM + wc * 32 + 8 * fq;
; #pragma unroll
;         for (int ai = 0; ai < 2; ++ai) { if (ai == 1 && u.q != 0) break;
; #pragma unroll
;             for (int m = 0; m < 4; ++m) { const int r = row0 + ai * HALF + m * 16; bf16_t* rowp = xb + (size_t)r * D + col0;
;                 const float* src = FIRST ? x0_row(xp, xs, meta, r) : nullptr; float ss = 0.f;
; #pragma unroll
;                 for (int bj = 0; bj < 2; ++bj) { f32x4 b0 = (f32x4){0.f, 0.f, 0.f, 0.f}, b1 = b0;
;                     if (FIRST) { if (src) { b0 = __builtin_nontemporal_load((const f32x4*)(src + col0 + bj * HALF)); b1 = __builtin_nontemporal_load((const f32x4*)(src + col0 + bj * HALF + 4)); } }
;                     else { const u32x4 w = *(const u32x4*)(rowp + bj * HALF);
;                         b0 = (f32x4){__uint_as_float(w.x << 16), __uint_as_float(w.x & 0xffff0000u), __uint_as_float(w.y << 16), __uint_as_float(w.y & 0xffff0000u)};
;                         b1 = (f32x4){__uint_as_float(w.z << 16), __uint_as_float(w.z & 0xffff0000u), __uint_as_float(w.w << 16), __uint_as_float(w.w & 0xffff0000u)}; }
;                     const f32x4 v0 = acc[ai][bj][m][0] + b0, v1 = acc[ai][bj][m][1] + b1;
;                     ss += ((v0[0] * v0[0] + v0[1] * v0[1]) + (v0[2] * v0[2] + v0[3] * v0[3])) + ((v1[0] * v1[0] + v1[1] * v1[1]) + (v1[2] * v1[2] + v1[3] * v1[3]));
;                     u32x4 o; o.x = cvt_pk_bf16(v0[0], v0[1]); o.y = cvt_pk_bf16(v0[2], v0[3]); o.z = cvt_pk_bf16(v1[0], v1[1]); o.w = cvt_pk_bf16(v1[2], v1[3]);
;                     *(u32x4*)(rowp + bj * HALF) = o; }
;                 if (rss) { ss += __shfl_xor(ss, 16); ss += __shfl_xor(ss, 32); if (fq == 0) atomicAdd(rss + r, ss); }
.LBB0_1493:
	s_nop 0
	v_add_co_u32_e32 v60, vcc, 0x48000, v134
	s_mov_b64 s[46:47], 0x48000
	s_nop 0
	v_addc_co_u32_e32 v61, vcc, 0, v135, vcc
	s_waitcnt lgkmcnt(0)
	global_load_dwordx4 v[54:57], v[60:61], off
	v_lshl_add_u64 v[58:59], v[134:135], 0, s[46:47]
	s_and_b64 vcc, exec, s[10:11]
	s_waitcnt vmcnt(0)
	v_lshlrev_b32_e32 v62, 16, v54
	v_and_b32_e32 v63, 0xffff0000, v54
	v_lshlrev_b32_e32 v54, 16, v55
	v_and_b32_e32 v55, 0xffff0000, v55
	v_lshlrev_b32_e32 v64, 16, v56
	v_and_b32_e32 v65, 0xffff0000, v56
	v_lshlrev_b32_e32 v66, 16, v57
	v_and_b32_e32 v67, 0xffff0000, v57
	v_pk_add_f32 v[54:55], v[48:49], v[54:55]
	v_pk_add_f32 v[56:57], v[46:47], v[62:63]
	v_pk_add_f32 v[46:47], v[52:53], v[66:67]
	v_pk_add_f32 v[48:49], v[50:51], v[64:65]
	v_cvt_pk_bf16_f32 v50, v56, v57
	v_cvt_pk_bf16_f32 v51, v54, v55
	v_cvt_pk_bf16_f32 v52, v48, v49
	v_cvt_pk_bf16_f32 v53, v46, v47
	global_store_dwordx4 v[60:61], v[50:53], off sc0 sc1
	global_load_dwordx4 v[50:53], v[58:59], off offset:256
	s_waitcnt vmcnt(0)
	v_lshlrev_b32_e32 v60, 16, v50
	v_and_b32_e32 v61, 0xffff0000, v50
	v_lshlrev_b32_e32 v50, 16, v51
	v_and_b32_e32 v51, 0xffff0000, v51
	v_lshlrev_b32_e32 v62, 16, v52
	v_and_b32_e32 v63, 0xffff0000, v52
	v_lshlrev_b32_e32 v64, 16, v53
	v_and_b32_e32 v65, 0xffff0000, v53
	v_pk_add_f32 v[50:51], v[40:41], v[50:51]
	v_pk_add_f32 v[52:53], v[38:39], v[60:61]
	v_pk_add_f32 v[38:39], v[44:45], v[64:65]
	v_pk_add_f32 v[40:41], v[42:43], v[62:63]
	v_cvt_pk_bf16_f32 v42, v52, v53
	v_cvt_pk_bf16_f32 v43, v50, v51
	v_cvt_pk_bf16_f32 v44, v40, v41
	v_cvt_pk_bf16_f32 v45, v38, v39
	global_store_dwordx4 v[58:59], v[42:45], off offset:256 sc0 sc1
	s_cbranch_vccnz .LBB0_1497
	v_mul_f32_e32 v18, v57, v57
	v_mul_f32_e32 v42, v55, v55
	v_fmac_f32_e32 v18, v56, v56
	v_fmac_f32_e32 v42, v54, v54
	v_add_f32_e32 v18, v18, v42
	v_mul_f32_e32 v42, v49, v49
	v_mul_f32_e32 v43, v47, v47
	v_fmac_f32_e32 v42, v48, v48
	v_fmac_f32_e32 v43, v46, v46
	v_add_f32_e32 v42, v42, v43
	v_add_f32_e32 v18, v18, v42
	v_mul_f32_e32 v42, v53, v53
	v_mul_f32_e32 v43, v51, v51
	v_mul_f32_e32 v41, v41, v41
	v_mul_f32_e32 v39, v39, v39
	v_fmac_f32_e32 v42, v52, v52
	v_fmac_f32_e32 v43, v50, v50
	v_fmac_f32_e32 v41, v40, v40
	v_fmac_f32_e32 v39, v38, v38
	v_add_f32_e32 v42, v42, v43
	v_add_f32_e32 v38, v41, v39
	v_add_f32_e32 v38, v42, v38
	v_and_b32_e32 v39, 64, v226
	v_add_f32_e32 v18, v18, v38
	v_xor_b32_e32 v38, 16, v226
	v_add_u32_e32 v39, 64, v39
	v_cmp_lt_i32_e32 vcc, v38, v39
	s_nop 1
	v_cndmask_b32_e32 v38, v226, v38, vcc
	v_lshlrev_b32_e32 v38, 2, v38
	ds_bpermute_b32 v38, v38, v18
	s_waitcnt lgkmcnt(0)
	v_add_f32_e32 v18, v18, v38
	v_xor_b32_e32 v38, 32, v226
	v_cmp_lt_i32_e32 vcc, v38, v39
	s_nop 1
	v_cndmask_b32_e32 v38, v226, v38, vcc
	v_lshlrev_b32_e32 v38, 2, v38
	ds_bpermute_b32 v38, v38, v18
	s_and_saveexec_b64 s[46:47], s[6:7]
	s_cbranch_execz .LBB0_1496
	v_lshl_add_u64 v[40:41], v[20:21], 2, s[24:25]
	s_waitcnt lgkmcnt(0)
	v_add_f32_e32 v18, v18, v38
	global_atomic_add_f32 v[40:41], v18, off offset:576

; __device__ __forceinline__ unsigned cvt_pk_bf16(float lo, float hi) { const bf16x2_t r = __builtin_convertvector((f32x2){lo, hi}, bf16x2_t); return __builtin_bit_cast(unsigned, r); }
;     __device__ __forceinline__ void operator()(f32x4 (&acc)[2][2][4][2], const Unit& u, int row0t, int wr, int wc, int fr, int fq) const {
;     ...
;         const int row0 = row0t + wr * 64 + fr, col0 = u.pn * BM + wc * 32 + 8 * fq;
; #pragma unroll
;         for (int ai = 0; ai < 2; ++ai) { if (ai == 1 && u.q != 0) break;
; #pragma unroll
;             for (int m = 0; m < 4; ++m) { const int r = row0 + ai * HALF + m * 16; bf16_t* rowp = xb + (size_t)r * D + col0;
;                 const float* src = FIRST ? x0_row(xp, xs, meta, r) : nullptr; float ss = 0.f;
; #pragma unroll
;                 for (int bj = 0; bj < 2; ++bj) { f32x4 b0 = (f32x4){0.f, 0.f, 0.f, 0.f}, b1 = b0;
;                     if (FIRST) { if (src) { b0 = __builtin_nontemporal_load((const f32x4*)(src + col0 + bj * HALF)); b1 = __builtin_nontemporal_load((const f32x4*)(src + col0 + bj * HALF + 4)); } }
;                     else { const u32x4 w = *(const u32x4*)(rowp + bj * HALF);
;                         b0 = (f32x4){__uint_as_float(w.x << 16), __uint_as_float(w.x & 0xffff0000u), __uint_as_float(w.y << 16), __uint_as_float(w.y & 0xffff0000u)};
;                         b1 = (f32x4){__uint_as_float(w.z << 16), __uint_as_float(w.z & 0xffff0000u), __uint_as_float(w.w << 16), __uint_as_float(w.w & 0xffff0000u)}; }
;                     const f32x4 v0 = acc[ai][bj][m][0] + b0, v1 = acc[ai][bj][m][1] + b1;
;                     ss += ((v0[0] * v0[0] + v0[1] * v0[1]) + (v0[2] * v0[2] + v0[3] * v0[3])) + ((v1[0] * v1[0] + v1[1] * v1[1]) + (v1[2] * v1[2] + v1[3] * v1[3]));
;                     u32x4 o; o.x = cvt_pk_bf16(v0[0], v0[1]); o.y = cvt_pk_bf16(v0[2], v0[3]); o.z = cvt_pk_bf16(v1[0], v1[1]); o.w = cvt_pk_bf16(v1[2], v1[3]);
;                     *(u32x4*)(rowp + bj * HALF) = o; }
;                 if (rss) { ss += __shfl_xor(ss, 16); ss += __shfl_xor(ss, 32); if (fq == 0) atomicAdd(rss + r, ss); }
.LBB0_1497:
	s_nop 0
	v_add_co_u32_e32 v44, vcc, 0x50000, v134
	s_mov_b64 s[46:47], 0x50000
	s_nop 0
	v_addc_co_u32_e32 v45, vcc, 0, v135, vcc
	s_waitcnt lgkmcnt(0)
	global_load_dwordx4 v[38:41], v[44:45], off
	v_lshl_add_u64 v[42:43], v[134:135], 0, s[46:47]
	s_and_b64 vcc, exec, s[10:11]
	s_waitcnt vmcnt(0)
	v_lshlrev_b32_e32 v46, 16, v38
	v_and_b32_e32 v47, 0xffff0000, v38
	v_lshlrev_b32_e32 v38, 16, v39
	v_and_b32_e32 v39, 0xffff0000, v39
	v_lshlrev_b32_e32 v48, 16, v40
	v_and_b32_e32 v49, 0xffff0000, v40
	v_lshlrev_b32_e32 v50, 16, v41
	v_and_b32_e32 v51, 0xffff0000, v41
	v_pk_add_f32 v[38:39], v[32:33], v[38:39]
	v_pk_add_f32 v[40:41], v[30:31], v[46:47]
	v_pk_add_f32 v[30:31], v[36:37], v[50:51]
	v_pk_add_f32 v[32:33], v[34:35], v[48:49]
	v_cvt_pk_bf16_f32 v34, v40, v41
	v_cvt_pk_bf16_f32 v35, v38, v39
	v_cvt_pk_bf16_f32 v36, v32, v33
	v_cvt_pk_bf16_f32 v37, v30, v31
	global_store_dwordx4 v[44:45], v[34:37], off sc0 sc1
	global_load_dwordx4 v[34:37], v[42:43], off offset:256
	s_waitcnt vmcnt(0)
	v_lshlrev_b32_e32 v44, 16, v34
	v_and_b32_e32 v45, 0xffff0000, v34
	v_lshlrev_b32_e32 v34, 16, v35
	v_and_b32_e32 v35, 0xffff0000, v35
	v_lshlrev_b32_e32 v46, 16, v36
	v_and_b32_e32 v47, 0xffff0000, v36
	v_lshlrev_b32_e32 v48, 16, v37
	v_and_b32_e32 v49, 0xffff0000, v37
	v_pk_add_f32 v[34:35], v[24:25], v[34:35]
	v_pk_add_f32 v[36:37], v[22:23], v[44:45]
	v_pk_add_f32 v[22:23], v[28:29], v[48:49]
	v_pk_add_f32 v[24:25], v[26:27], v[46:47]
	v_cvt_pk_bf16_f32 v26, v36, v37
	v_cvt_pk_bf16_f32 v27, v34, v35
	v_cvt_pk_bf16_f32 v28, v24, v25
	v_cvt_pk_bf16_f32 v29, v22, v23
	global_store_dwordx4 v[42:43], v[26:29], off offset:256 sc0 sc1
	s_cbranch_vccnz .LBB0_1501
	v_mul_f32_e32 v18, v41, v41
	v_mul_f32_e32 v26, v39, v39
	v_fmac_f32_e32 v18, v40, v40
	v_fmac_f32_e32 v26, v38, v38
	v_add_f32_e32 v18, v18, v26
	v_mul_f32_e32 v26, v33, v33
	v_mul_f32_e32 v27, v31, v31
	v_fmac_f32_e32 v26, v32, v32
	v_fmac_f32_e32 v27, v30, v30
	v_add_f32_e32 v26, v26, v27
	v_add_f32_e32 v18, v18, v26
	v_mul_f32_e32 v26, v37, v37
	v_mul_f32_e32 v27, v35, v35
	v_mul_f32_e32 v25, v25, v25
	v_mul_f32_e32 v23, v23, v23
	v_fmac_f32_e32 v26, v36, v36
	v_fmac_f32_e32 v27, v34, v34
	v_fmac_f32_e32 v25, v24, v24
	v_fmac_f32_e32 v23, v22, v22
	v_add_f32_e32 v26, v26, v27
	v_add_f32_e32 v22, v25, v23
	v_add_f32_e32 v22, v26, v22
	v_and_b32_e32 v23, 64, v226
	v_add_f32_e32 v18, v18, v22
	v_xor_b32_e32 v22, 16, v226
	v_add_u32_e32 v23, 64, v23
	v_cmp_lt_i32_e32 vcc, v22, v23
	s_nop 1
	v_cndmask_b32_e32 v22, v226, v22, vcc
	v_lshlrev_b32_e32 v22, 2, v22
	ds_bpermute_b32 v22, v22, v18
	s_waitcnt lgkmcnt(0)
	v_add_f32_e32 v18, v18, v22
	v_xor_b32_e32 v22, 32, v226
	v_cmp_lt_i32_e32 vcc, v22, v23
	s_nop 1
	v_cndmask_b32_e32 v22, v226, v22, vcc
	v_lshlrev_b32_e32 v22, 2, v22
	ds_bpermute_b32 v22, v22, v18
	s_and_saveexec_b64 s[46:47], s[6:7]
	s_cbranch_execz .LBB0_1500
	v_lshl_add_u64 v[24:25], v[20:21], 2, s[24:25]
	s_waitcnt lgkmcnt(0)
	v_add_f32_e32 v18, v18, v22
	global_atomic_add_f32 v[24:25], v18, off offset:640

; __device__ __forceinline__ unsigned cvt_pk_bf16(float lo, float hi) { const bf16x2_t r = __builtin_convertvector((f32x2){lo, hi}, bf16x2_t); return __builtin_bit_cast(unsigned, r); }
;     __device__ __forceinline__ void operator()(f32x4 (&acc)[2][2][4][2], const Unit& u, int row0t, int wr, int wc, int fr, int fq) const {
;     ...
;         const int row0 = row0t + wr * 64 + fr, col0 = u.pn * BM + wc * 32 + 8 * fq;
; #pragma unroll
;         for (int ai = 0; ai < 2; ++ai) { if (ai == 1 && u.q != 0) break;
; #pragma unroll
;             for (int m = 0; m < 4; ++m) { const int r = row0 + ai * HALF + m * 16; bf16_t* rowp = xb + (size_t)r * D + col0;
;                 const float* src = FIRST ? x0_row(xp, xs, meta, r) : nullptr; float ss = 0.f;
; #pragma unroll
;                 for (int bj = 0; bj < 2; ++bj) { f32x4 b0 = (f32x4){0.f, 0.f, 0.f, 0.f}, b1 = b0;
;                     if (FIRST) { if (src) { b0 = __builtin_nontemporal_load((const f32x4*)(src + col0 + bj * HALF)); b1 = __builtin_nontemporal_load((const f32x4*)(src + col0 + bj * HALF + 4)); } }
;                     else { const u32x4 w = *(const u32x4*)(rowp + bj * HALF);
;                         b0 = (f32x4){__uint_as_float(w.x << 16), __uint_as_float(w.x & 0xffff0000u), __uint_as_float(w.y << 16), __uint_as_float(w.y & 0xffff0000u)};
;                         b1 = (f32x4){__uint_as_float(w.z << 16), __uint_as_float(w.z & 0xffff0000u), __uint_as_float(w.w << 16), __uint_as_float(w.w & 0xffff0000u)}; }
;                     const f32x4 v0 = acc[ai][bj][m][0] + b0, v1 = acc[ai][bj][m][1] + b1;
;                     ss += ((v0[0] * v0[0] + v0[1] * v0[1]) + (v0[2] * v0[2] + v0[3] * v0[3])) + ((v1[0] * v1[0] + v1[1] * v1[1]) + (v1[2] * v1[2] + v1[3] * v1[3]));
;                     u32x4 o; o.x = cvt_pk_bf16(v0[0], v0[1]); o.y = cvt_pk_bf16(v0[2], v0[3]); o.z = cvt_pk_bf16(v1[0], v1[1]); o.w = cvt_pk_bf16(v1[2], v1[3]);
;                     *(u32x4*)(rowp + bj * HALF) = o; }
;                 if (rss) { ss += __shfl_xor(ss, 16); ss += __shfl_xor(ss, 32); if (fq == 0) atomicAdd(rss + r, ss); }
.LBB0_1501:
	s_nop 0
	v_add_co_u32_e32 v28, vcc, 0x58000, v134
	s_mov_b64 s[46:47], 0x58000
	s_nop 0
	v_addc_co_u32_e32 v29, vcc, 0, v135, vcc
	s_waitcnt lgkmcnt(0)
	global_load_dwordx4 v[22:25], v[28:29], off
	v_lshl_add_u64 v[26:27], v[134:135], 0, s[46:47]
	s_and_b64 vcc, exec, s[10:11]
	s_waitcnt vmcnt(0)
	v_lshlrev_b32_e32 v30, 16, v22
	v_and_b32_e32 v31, 0xffff0000, v22
	v_lshlrev_b32_e32 v22, 16, v23
	v_and_b32_e32 v23, 0xffff0000, v23
	v_lshlrev_b32_e32 v32, 16, v24
	v_and_b32_e32 v33, 0xffff0000, v24
	v_lshlrev_b32_e32 v34, 16, v25
	v_and_b32_e32 v35, 0xffff0000, v25
	v_pk_add_f32 v[22:23], v[12:13], v[22:23]
	v_pk_add_f32 v[24:25], v[10:11], v[30:31]
	v_pk_add_f32 v[10:11], v[16:17], v[34:35]
	v_pk_add_f32 v[12:13], v[14:15], v[32:33]
	v_cvt_pk_bf16_f32 v14, v24, v25
	v_cvt_pk_bf16_f32 v15, v22, v23
	v_cvt_pk_bf16_f32 v16, v12, v13
	v_cvt_pk_bf16_f32 v17, v10, v11
	global_store_dwordx4 v[28:29], v[14:17], off sc0 sc1
	global_load_dwordx4 v[14:17], v[26:27], off offset:256
	s_waitcnt vmcnt(0)
	v_lshlrev_b32_e32 v28, 16, v14
	v_and_b32_e32 v29, 0xffff0000, v14
	v_lshlrev_b32_e32 v14, 16, v15
	v_and_b32_e32 v15, 0xffff0000, v15
	v_lshlrev_b32_e32 v30, 16, v16
	v_and_b32_e32 v31, 0xffff0000, v16
	v_lshlrev_b32_e32 v32, 16, v17
	v_and_b32_e32 v33, 0xffff0000, v17
	v_pk_add_f32 v[14:15], v[4:5], v[14:15]
	v_pk_add_f32 v[16:17], v[2:3], v[28:29]
	v_pk_add_f32 v[2:3], v[8:9], v[32:33]
	v_pk_add_f32 v[4:5], v[6:7], v[30:31]
	v_cvt_pk_bf16_f32 v6, v16, v17
	v_cvt_pk_bf16_f32 v7, v14, v15
	v_cvt_pk_bf16_f32 v8, v4, v5
	v_cvt_pk_bf16_f32 v9, v2, v3
	global_store_dwordx4 v[26:27], v[6:9], off offset:256 sc0 sc1
	s_cbranch_vccnz .LBB0_1505
	s_nop 0
	v_mul_f32_e32 v6, v25, v25
	v_mul_f32_e32 v7, v23, v23
	v_fmac_f32_e32 v6, v24, v24
	v_fmac_f32_e32 v7, v22, v22
	v_add_f32_e32 v6, v6, v7
	v_mul_f32_e32 v7, v13, v13
	v_mul_f32_e32 v8, v11, v11
	v_fmac_f32_e32 v7, v12, v12
	v_fmac_f32_e32 v8, v10, v10
	v_add_f32_e32 v7, v7, v8
	v_mul_f32_e32 v5, v5, v5
	v_mul_f32_e32 v3, v3, v3
	v_add_f32_e32 v6, v6, v7
	v_mul_f32_e32 v7, v17, v17
	v_mul_f32_e32 v8, v15, v15
	v_fmac_f32_e32 v5, v4, v4
	v_fmac_f32_e32 v3, v2, v2
	v_and_b32_e32 v4, 64, v226
	v_fmac_f32_e32 v7, v16, v16
	v_fmac_f32_e32 v8, v14, v14
	v_add_f32_e32 v2, v5, v3
	v_xor_b32_e32 v3, 16, v226
	v_add_u32_e32 v4, 64, v4
	v_add_f32_e32 v7, v7, v8
	v_cmp_lt_i32_e32 vcc, v3, v4
	v_add_f32_e32 v2, v7, v2
	v_add_f32_e32 v2, v6, v2
	v_cndmask_b32_e32 v3, v226, v3, vcc
	v_lshlrev_b32_e32 v3, 2, v3
	ds_bpermute_b32 v3, v3, v2
	s_waitcnt lgkmcnt(0)
	v_add_f32_e32 v2, v2, v3
	v_xor_b32_e32 v3, 32, v226
	v_cmp_lt_i32_e32 vcc, v3, v4
	s_nop 1
	v_cndmask_b32_e32 v3, v226, v3, vcc
	v_lshlrev_b32_e32 v3, 2, v3
	ds_bpermute_b32 v3, v3, v2
	s_and_saveexec_b64 s[10:11], s[6:7]
	s_cbranch_execz .LBB0_1504
	v_lshl_add_u64 v[4:5], v[20:21], 2, s[24:25]
	s_waitcnt lgkmcnt(0)
	v_add_f32_e32 v2, v2, v3
	global_atomic_add_f32 v[4:5], v2, off offset:704

; #define GRID_SYNC() xcd_barrier(xbar)
; template <class RecFn>
; __device__ __forceinline__ void gdn_scan(LAS unsigned char* lds, int bh, int b0, RecFn rec_of, const float* gtarr, bf16_t* zb, const float* gnorm_w, float* Sout, const unsigned* late_cnt, unsigned late_need, int cwait) {
;     ...
;     auto late_wait = [&]() {
;         if (threadIdx.x == 0) { unsigned polls = 0;
;             while (__hip_atomic_load(late_cnt, __ATOMIC_RELAXED, __HIP_MEMORY_SCOPE_AGENT) < late_need) { if (++polls > (1u << 20)) break; __builtin_amdgcn_s_sleep(8); }
;             __builtin_amdgcn_fence(__ATOMIC_ACQUIRE, "agent"); asm volatile("s_waitcnt vmcnt(0)" ::: "memory"); }
;         __syncthreads(); };
; __global__ void __launch_bounds__(NTHREADS, 2) fwd_megakernel(Params p) {
;     ...
;             pg8::gemm_phase<pg8::EpiRes<false>, true, true, pg8::TailOrder>(lds, g, S, E);
;         }
;         GRID_SYNC();
.LBB0_1507:
	v_readlane_b32 s98, v239, 0
	s_nop 3
	s_cmp_lg_u32 s98, 0
	s_cbranch_scc1 .Lfn_skip
	s_cmp_lt_u32 s94, 80
	s_cbranch_scc1 .Lfn_skip
	s_waitcnt vmcnt(0)
	s_barrier
	v_cmp_eq_u32_e32 vcc, 0, v0
	s_nop 3
	s_mov_b64 exec, vcc
	s_cbranch_execz .Lfn_a2_x
	v_readlane_b32 s98, v245, 33
	v_readlane_b32 s99, v245, 34
	v_mov_b32_e32 v247, 0
	v_mov_b32_e32 v248, 1
	s_nop 3
	s_add_u32 s98, s98, 0xc000
	s_addc_u32 s99, s99, 0
	global_atomic_add v247, v248, s[98:99]
	s_movk_i32 s100, 0x4000
.Lfn_poll:
	global_load_dword v248, v247, s[98:99] sc1
	s_waitcnt vmcnt(0)
	v_readfirstlane_b32 s101, v248
	s_nop 3
	s_cmpk_ge_u32 s101, 0x100
	s_cbranch_scc1 .Lfn_acq
	s_sleep 2
	s_add_i32 s100, s100, -1
	s_cmp_lg_u32 s100, 0
	s_cbranch_scc1 .Lfn_poll

; #define PHASE_IDS() const int tid = fresh_tid(), lane = tid & 63, wave = __builtin_amdgcn_readfirstlane(tid >> 6), gw = bx * NWAVES + wave; (void)lane; (void)gw
; __global__ void __launch_bounds__(NTHREADS, 2) fwd_megakernel(Params p) {
;     ...
;     { PHASE_IDS();
;     auto ld_row = [&](int r, u32x4 (&w)[2]) { if (r < T) { const u32x4* xr = (const u32x4*)(xb + (size_t)r * D) + lane; w[0] = xr[0]; w[1] = xr[64]; } };
;     u32x4 nw[2] = {(u32x4){0u, 0u, 0u, 0u}, (u32x4){0u, 0u, 0u, 0u}}; ld_row(gw, nw);
;     for (int r = gw; r < T; r += NGW) {
;         u32x4 cw2[2] = {nw[0], nw[1]};
;         ld_row(r + NGW, nw);
;         float* dst;
;         if (r < NPROMPT) { const int b = r / LP, t = r - b * LP; if (t < NMETA) continue; dst = out + O_YP + ((size_t)b * SEQ + (t - NMETA)) * D; }
;         else dst = out + O_YS + (size_t)(r - NPROMPT) * D;
.Lfn_a2_x:
	s_mov_b64 exec, -1
	s_barrier
	v_writelane_b32 v247, s3, 0
	v_writelane_b32 v247, s10, 1
	v_writelane_b32 v247, s11, 2
	v_writelane_b32 v247, s12, 3
	v_writelane_b32 v247, s13, 4
	v_writelane_b32 v247, s15, 5
	s_movk_i32 s100, 1408
	s_sub_i32 s1, s94, 80
	s_lshl_b32 s1, s1, 3
	v_readfirstlane_b32 s0, v0
	s_ashr_i32 s0, s0, 6
	s_add_i32 s2, s0, s1
	s_cmpk_gt_i32 s2, 0x3fff
	s_cbranch_scc1 .Lfn_exit
	s_ashr_i32 s3, s2, 31
	s_lshl_b64 s[0:1], s[2:3], 11
	v_and_b32_e32 v63, 63, v0
	s_add_u32 s0, s44, s0
	s_addc_u32 s1, s45, s1
	v_lshlrev_b32_e32 v60, 4, v63
	global_load_dwordx4 v[68:71], v60, s[0:1] offset:1024
	global_load_dwordx4 v[72:75], v60, s[0:1]
	s_add_u32 s13, s88, 0x4000000
	s_addc_u32 s14, s89, 0
	s_add_i32 s0, s2, 0xffffbf80
	s_add_i32 s2, s2, s100
	s_ashr_i32 s3, s2, 31
	s_lshl_b64 s[2:3], s[2:3], 11
	s_add_u32 s2, s90, s2
	v_mov_b32_e32 v61, 0
	s_addc_u32 s3, s91, s3
	s_mov_b64 s[4:5], 0x4a00000
	v_and_b32_e32 v66, 64, v226
	v_lshlrev_b32_e32 v62, 3, v63
	v_lshlrev_b32_e32 v64, 5, v63
	v_mov_b32_e32 v65, v61
	v_lshl_add_u64 v[60:61], s[2:3], 0, v[60:61]
	v_add_u32_e32 v87, 64, v66
	v_lshl_add_u64 v[76:77], s[86:87], 0, v[64:65]
	v_lshlrev_b32_e32 v88, 2, v62
	s_ashr_i32 s101, s100, 31
	v_lshl_add_u64 v[78:79], v[60:61], 0, s[4:5]
	s_mov_b32 s1, 0
	v_mov_b32_e32 v80, 0x358637bd
	s_mov_b32 s12, 0x800000
	v_xor_b32_e32 v81, 1, v226
	v_xor_b32_e32 v82, 2, v226
	v_xor_b32_e32 v83, 4, v226
	v_xor_b32_e32 v84, 8, v226
	v_xor_b32_e32 v85, 16, v226
	v_xor_b32_e32 v86, 32, v226
	s_lshl_b64 s[2:3], s[100:101], 11
	s_waitcnt vmcnt(1)
	v_mov_b64_e32 v[60:61], v[68:69]
	s_waitcnt vmcnt(0)
	v_mov_b64_e32 v[64:65], v[72:73]
	v_mov_b64_e32 v[62:63], v[70:71]
	v_mov_b64_e32 v[66:67], v[74:75]
	s_branch .Lfn_b07
.Lfn_b06:
	s_waitcnt vmcnt(1)
	v_mov_b64_e32 v[74:75], v[66:67]
	s_waitcnt vmcnt(0)
	v_mov_b64_e32 v[70:71], v[62:63]
	v_lshl_add_u64 v[78:79], v[78:79], 0, s[2:3]
	s_and_b64 vcc, exec, s[4:5]
	s_mov_b32 s0, s15
	v_mov_b64_e32 v[72:73], v[64:65]
	v_mov_b64_e32 v[68:69], v[60:61]
	s_cbranch_vccnz .Lfn_exit
.Lfn_b07:
	s_add_i32 s15, s100, s0
	s_add_i32 s4, s15, 0x4080
	s_cmpk_gt_i32 s4, 0x3fff
	s_cselect_b64 s[4:5], -1, 0
	s_and_b64 vcc, exec, s[4:5]
	s_cbranch_vccnz .Lfn_b09
	global_load_dwordx4 v[64:67], v[78:79], off
	global_load_dwordx4 v[60:63], v[78:79], off offset:1024

; __global__ void __launch_bounds__(NTHREADS, 2) fwd_megakernel(Params p) {
;     ...
;         float f[2][8]; float s = 0.f;
; #pragma unroll
;         for (int j = 0; j < 2; ++j) { const unsigned ww[4] = {cw2[j].x, cw2[j].y, cw2[j].z, cw2[j].w};
; #pragma unroll
;             for (int e = 0; e < 4; ++e) { f[j][2 * e] = __uint_as_float(ww[e] << 16); f[j][2 * e + 1] = __uint_as_float(ww[e] & 0xffff0000u); s += f[j][2 * e] * f[j][2 * e] + f[j][2 * e + 1] * f[j][2 * e + 1]; } }
;         const float rstd = rsqrtf(wave_sum(s) * (1.f / D) + EPS);
; #pragma unroll
;         for (int j = 0; j < 2; ++j) { const int c = 8 * lane + 512 * j; const f32x4 wa = *(const f32x4*)(norm_final + c), wb = *(const f32x4*)(norm_final + c + 4);
;             *(f32x4*)(dst + c) = (f32x4){f[j][0], f[j][1], f[j][2], f[j][3]} * rstd * wa; *(f32x4*)(dst + c + 4) = (f32x4){f[j][4], f[j][5], f[j][6], f[j][7]} * rstd * wb; }
.Lfn_b13:
	s_andn2_b64 vcc, exec, s[8:9]
	s_cbranch_vccnz .Lfn_b06
	v_and_b32_e32 v95, 0xffff0000, v72
	v_and_b32_e32 v97, 0xffff0000, v73
	v_lshlrev_b32_e32 v94, 16, v72
	v_mul_f32_e32 v72, v95, v95
	v_lshlrev_b32_e32 v96, 16, v73
	v_mul_f32_e32 v73, v97, v97
	v_fmac_f32_e32 v72, v94, v94
	v_fmac_f32_e32 v73, v96, v96
	v_and_b32_e32 v99, 0xffff0000, v74
	v_add_f32_e32 v72, v72, v73
	v_lshlrev_b32_e32 v98, 16, v74
	v_mul_f32_e32 v73, v99, v99
	v_fmac_f32_e32 v73, v98, v98
	v_and_b32_e32 v101, 0xffff0000, v75
	v_add_f32_e32 v72, v72, v73
	v_lshlrev_b32_e32 v100, 16, v75
	v_mul_f32_e32 v73, v101, v101
	v_fmac_f32_e32 v73, v100, v100
	v_add_f32_e32 v89, v72, v73
	global_load_dwordx4 v[72:75], v[76:77], off offset:16
	global_load_dwordx4 v[90:93], v[76:77], off
	v_and_b32_e32 v105, 0xffff0000, v69
	v_and_b32_e32 v104, 0xffff0000, v68
	v_lshlrev_b32_e32 v103, 16, v69
	v_lshlrev_b32_e32 v102, 16, v68
	v_pk_mul_f32 v[68:69], v[104:105], v[104:105]
	v_and_b32_e32 v109, 0xffff0000, v71
	v_pk_fma_f32 v[68:69], v[102:103], v[102:103], v[68:69]
	v_and_b32_e32 v108, 0xffff0000, v70
	v_add_f32_e32 v68, v89, v68
	v_add_f32_e32 v89, v68, v69
	v_lshlrev_b32_e32 v107, 16, v71
	v_lshlrev_b32_e32 v106, 16, v70
	v_pk_mul_f32 v[68:69], v[108:109], v[108:109]
	v_cmp_lt_i32_e32 vcc, v81, v87
	v_pk_fma_f32 v[68:69], v[106:107], v[106:107], v[68:69]
	s_nop 0
	v_add_f32_e32 v68, v89, v68
	v_add_f32_e32 v68, v68, v69
	v_cndmask_b32_e32 v69, v226, v81, vcc
	v_lshlrev_b32_e32 v69, 2, v69
	ds_bpermute_b32 v69, v69, v68
	v_cmp_lt_i32_e32 vcc, v82, v87
	s_waitcnt lgkmcnt(0)
	v_add_f32_e32 v68, v68, v69
	v_cndmask_b32_e32 v69, v226, v82, vcc
	v_lshlrev_b32_e32 v69, 2, v69
	ds_bpermute_b32 v69, v69, v68
	v_cmp_lt_i32_e32 vcc, v83, v87
	s_waitcnt lgkmcnt(0)
	v_add_f32_e32 v68, v68, v69
	v_cndmask_b32_e32 v69, v226, v83, vcc
	v_lshlrev_b32_e32 v69, 2, v69
	ds_bpermute_b32 v69, v69, v68
	v_cmp_lt_i32_e32 vcc, v84, v87
	s_waitcnt lgkmcnt(0)
	v_add_f32_e32 v68, v68, v69
	v_cndmask_b32_e32 v69, v226, v84, vcc
	v_lshlrev_b32_e32 v69, 2, v69
	ds_bpermute_b32 v69, v69, v68
	v_cmp_lt_i32_e32 vcc, v85, v87
	s_waitcnt lgkmcnt(0)
	v_add_f32_e32 v68, v68, v69
	v_cndmask_b32_e32 v69, v226, v85, vcc
	v_lshlrev_b32_e32 v69, 2, v69
	ds_bpermute_b32 v69, v69, v68
	v_cmp_lt_i32_e32 vcc, v86, v87
	s_waitcnt lgkmcnt(0)
	v_add_f32_e32 v68, v68, v69
	v_cndmask_b32_e32 v69, v226, v86, vcc
	v_lshlrev_b32_e32 v69, 2, v69
	ds_bpermute_b32 v69, v69, v68
	s_waitcnt lgkmcnt(0)
	v_add_f32_e32 v68, v68, v69
	v_fmamk_f32 v68, v68, 0x3a800000, v80
	v_mul_f32_e32 v69, 0x4b800000, v68
	v_cmp_gt_f32_e32 vcc, s12, v68
	s_nop 1
	v_cndmask_b32_e32 v68, v68, v69, vcc
	v_rsq_f32_e32 v68, v68
	s_nop 0
	v_mul_f32_e32 v69, 0x45800000, v68
	v_cndmask_b32_e32 v110, v68, v69, vcc
	v_pk_mul_f32 v[68:69], v[110:111], v[94:95] op_sel_hi:[0,1]
	v_pk_mul_f32 v[70:71], v[110:111], v[96:97] op_sel_hi:[0,1]
	v_pk_mul_f32 v[94:95], v[110:111], v[98:99] op_sel_hi:[0,1]
	v_pk_mul_f32 v[96:97], v[110:111], v[100:101] op_sel_hi:[0,1]
	s_waitcnt vmcnt(0)
	v_pk_mul_f32 v[70:71], v[92:93], v[70:71]
	v_pk_mul_f32 v[68:69], v[90:91], v[68:69]
	v_pk_mul_f32 v[74:75], v[74:75], v[96:97]
	v_pk_mul_f32 v[72:73], v[72:73], v[94:95]
	global_store_dwordx4 v88, v[68:71], s[6:7]
	global_store_dwordx4 v88, v[72:75], s[6:7] offset:16
	global_load_dwordx4 v[68:71], v[76:77], off offset:2048
	s_nop 0
	global_load_dwordx4 v[72:75], v[76:77], off offset:2064
	v_mov_b32_e32 v90, v103
	v_mov_b32_e32 v91, v105
	v_mov_b32_e32 v103, v104
	v_mov_b32_e32 v92, v107
	v_mov_b32_e32 v93, v109
	v_mov_b32_e32 v107, v108
	v_pk_mul_f32 v[90:91], v[110:111], v[90:91] op_sel_hi:[0,1]
	v_pk_mul_f32 v[94:95], v[110:111], v[102:103] op_sel_hi:[0,1]
	v_pk_mul_f32 v[92:93], v[110:111], v[92:93] op_sel_hi:[0,1]
	v_pk_mul_f32 v[96:97], v[110:111], v[106:107] op_sel_hi:[0,1]
	s_waitcnt vmcnt(1)
	v_pk_mul_f32 v[68:69], v[68:69], v[94:95]
	v_pk_mul_f32 v[70:71], v[70:71], v[90:91]
	s_waitcnt vmcnt(0)
	v_pk_mul_f32 v[72:73], v[72:73], v[96:97]
	v_pk_mul_f32 v[74:75], v[74:75], v[92:93]
	global_store_dwordx4 v88, v[68:71], s[6:7] offset:2048
	global_store_dwordx4 v88, v[72:75], s[6:7] offset:2064
	s_branch .Lfn_b06
.Lfn_exit:
	v_readlane_b32 s3, v247, 0
	v_readlane_b32 s10, v247, 1
	v_readlane_b32 s11, v247, 2
	v_readlane_b32 s12, v247, 3
	v_readlane_b32 s13, v247, 4
	v_readlane_b32 s15, v247, 5

; #define PHASE_IDS() const int tid = fresh_tid(), lane = tid & 63, wave = __builtin_amdgcn_readfirstlane(tid >> 6), gw = bx * NWAVES + wave; (void)lane; (void)gw
; __global__ void __launch_bounds__(NTHREADS, 2) fwd_megakernel(Params p) {
;     ...
;     { PHASE_IDS();
;     auto ld_row = [&](int r, u32x4 (&w)[2]) { if (r < T) { const u32x4* xr = (const u32x4*)(xb + (size_t)r * D) + lane; w[0] = xr[0]; w[1] = xr[64]; } };
;     u32x4 nw[2] = {(u32x4){0u, 0u, 0u, 0u}, (u32x4){0u, 0u, 0u, 0u}}; ld_row(gw, nw);
;     for (int r = gw; r < T; r += NGW) {
;         u32x4 cw2[2] = {nw[0], nw[1]};
;         ld_row(r + NGW, nw);
.LBB0_1904:
	v_readlane_b32 s1, v245, 49
	v_readfirstlane_b32 s0, v0
	s_ashr_i32 s0, s0, 6
	s_add_i32 s2, s0, s1
	s_addk_i32 s2, 0x4000
	s_cmpk_gt_i32 s2, 0x447f
	s_cbranch_scc1 .LBB0_1915
	s_ashr_i32 s3, s2, 31
	s_lshl_b64 s[0:1], s[2:3], 11
	v_and_b32_e32 v3, 63, v0
	s_add_u32 s0, s44, s0
	s_addc_u32 s1, s45, s1
	v_lshlrev_b32_e32 v0, 4, v3
	global_load_dwordx4 v[8:11], v0, s[0:1] offset:1024
	global_load_dwordx4 v[12:15], v0, s[0:1]
	s_add_u32 s13, s88, 0x4000000
	s_addc_u32 s14, s89, 0
	s_add_i32 s0, s2, 0xffffbf80
	s_add_i32 s2, s2, s92
	s_ashr_i32 s3, s2, 31
	s_lshl_b64 s[2:3], s[2:3], 11
	s_add_u32 s2, s90, s2
	v_mov_b32_e32 v1, 0
	s_addc_u32 s3, s91, s3
	s_mov_b64 s[4:5], 0x4a00000
	v_and_b32_e32 v6, 64, v226
	v_lshlrev_b32_e32 v2, 3, v3
	v_lshlrev_b32_e32 v4, 5, v3
	v_mov_b32_e32 v5, v1
	v_lshl_add_u64 v[0:1], s[2:3], 0, v[0:1]
	v_add_u32_e32 v27, 64, v6
	v_lshl_add_u64 v[16:17], s[86:87], 0, v[4:5]
	v_lshlrev_b32_e32 v28, 2, v2
	s_ashr_i32 s93, s92, 31
	v_lshl_add_u64 v[18:19], v[0:1], 0, s[4:5]
	s_mov_b32 s1, 0
	v_mov_b32_e32 v20, 0x358637bd
	s_mov_b32 s12, 0x800000
	v_xor_b32_e32 v21, 1, v226
	v_xor_b32_e32 v22, 2, v226
	v_xor_b32_e32 v23, 4, v226
	v_xor_b32_e32 v24, 8, v226
	v_xor_b32_e32 v25, 16, v226
	v_xor_b32_e32 v26, 32, v226
	s_lshl_b64 s[2:3], s[92:93], 11
	s_waitcnt vmcnt(1)
	v_mov_b64_e32 v[0:1], v[8:9]
	s_waitcnt vmcnt(0)
	v_mov_b64_e32 v[4:5], v[12:13]
	v_mov_b64_e32 v[2:3], v[10:11]
	v_mov_b64_e32 v[6:7], v[14:15]
	s_branch .LBB0_1907

; __global__ void __launch_bounds__(NTHREADS, 2) fwd_megakernel(Params p) {
	.amdhsa_kernel _Z14fwd_megakernel6Params
		.amdhsa_group_segment_fixed_size 0
		.amdhsa_private_segment_fixed_size 0
		.amdhsa_kernarg_size 448
		.amdhsa_user_sgpr_count 2
		.amdhsa_user_sgpr_dispatch_ptr 0
		.amdhsa_user_sgpr_queue_ptr 0
		.amdhsa_user_sgpr_kernarg_segment_ptr 1
		.amdhsa_user_sgpr_dispatch_id 0
		.amdhsa_user_sgpr_kernarg_preload_length 0
		.amdhsa_user_sgpr_kernarg_preload_offset 0
		.amdhsa_user_sgpr_private_segment_size 0
		.amdhsa_uses_dynamic_stack 0
		.amdhsa_enable_private_segment 0
		.amdhsa_system_sgpr_workgroup_id_x 1
		.amdhsa_system_sgpr_workgroup_id_y 0
		.amdhsa_system_sgpr_workgroup_id_z 0
		.amdhsa_system_sgpr_workgroup_info 0
		.amdhsa_system_vgpr_workitem_id 0
		.amdhsa_next_free_vgpr 252
		.amdhsa_next_free_sgpr 102
		.amdhsa_accum_offset 252
		.amdhsa_reserve_vcc 1
		.amdhsa_float_round_mode_32 0
		.amdhsa_float_round_mode_16_64 0
		.amdhsa_float_denorm_mode_32 3
		.amdhsa_float_denorm_mode_16_64 3
		.amdhsa_dx10_clamp 1
		.amdhsa_ieee_mode 1
		.amdhsa_fp16_overflow 0
		.amdhsa_tg_split 0
		.amdhsa_exception_fp_ieee_invalid_op 0
		.amdhsa_exception_fp_denorm_src 0
		.amdhsa_exception_fp_ieee_div_zero 0
		.amdhsa_exception_fp_ieee_overflow 0
		.amdhsa_exception_fp_ieee_underflow 0
		.amdhsa_exception_fp_ieee_inexact 0
		.amdhsa_exception_int_div_zero 0
	.end_amdhsa_kernel

; __global__ void __launch_bounds__(NTHREADS, 2) fwd_megakernel(Params p) {
amdhsa.kernels:
  - .agpr_count:     0
    .args:
      - .offset:         0
        .size:           192
        .value_kind:     by_value
      - .offset:         192
        .size:           4
        .value_kind:     hidden_block_count_x
      - .offset:         196
        .size:           4
        .value_kind:     hidden_block_count_y
      - .offset:         200
        .size:           4
        .value_kind:     hidden_block_count_z
      - .offset:         204
        .size:           2
        .value_kind:     hidden_group_size_x
      - .offset:         206
        .size:           2
        .value_kind:     hidden_group_size_y
      - .offset:         208
        .size:           2
        .value_kind:     hidden_group_size_z
      - .offset:         210
        .size:           2
        .value_kind:     hidden_remainder_x
      - .offset:         212
        .size:           2
        .value_kind:     hidden_remainder_y
      - .offset:         214
        .size:           2
        .value_kind:     hidden_remainder_z
      - .offset:         232
        .size:           8
        .value_kind:     hidden_global_offset_x
      - .offset:         240
        .size:           8
        .value_kind:     hidden_global_offset_y
      - .offset:         248
        .size:           8
        .value_kind:     hidden_global_offset_z
      - .offset:         256
        .size:           2
        .value_kind:     hidden_grid_dims
      - .offset:         312
        .size:           4
        .value_kind:     hidden_dynamic_lds_size
    .group_segment_fixed_size: 0
    .kernarg_segment_align: 8
    .kernarg_segment_size: 448
    .language:       OpenCL C
    .language_version:
      - 2
      - 0
    .max_flat_workgroup_size: 512
    .name:           _Z14fwd_megakernel6Params
    .private_segment_fixed_size: 0
    .sgpr_count:     108
    .sgpr_spill_count: 192
    .symbol:         _Z14fwd_megakernel6Params.kd
    .uniform_work_group_size: 1
    .uses_dynamic_stack: false
    .vgpr_count:     252
    .vgpr_spill_count: 0
    .wavefront_size: 64
